# attention PV: exact counted lgkmcnt before each MFMA instead of lgkmcnt(0) per tr-read group; p0 exps before barrier
# speedup vs baseline: 1.0043x; 1.0043x over previous
; #define SBAR() __builtin_amdgcn_sched_barrier(0)
; template <int OFF> __device__ __forceinline__ s16x4 tr_read(int vb) {
;   s16x4 r; asm volatile("ds_read_b64_tr_b16 %0, %1 offset:%2" : "=&v"(r) : "v"(vb), "i"(OFF) : "memory"); return r;
; }
; template <int D0> __device__ __forceinline__ void pv_one(f32x16& od, int vb, bf16x8 pa0, bf16x8 pa1, bf16x8 pa2, bf16x8 pa3) {
;   const s16x4 l0 = tr_read<v_rd_off(D0, 0, 0)>(vb), h0 = tr_read<v_rd_off(D0, 0, 1)>(vb), l1 = tr_read<v_rd_off(D0, 1, 0)>(vb), h1 = tr_read<v_rd_off(D0, 1, 1)>(vb);
;   const s16x4 l2 = tr_read<v_rd_off(D0, 2, 0)>(vb), h2 = tr_read<v_rd_off(D0, 2, 1)>(vb), l3 = tr_read<v_rd_off(D0, 3, 0)>(vb), h3 = tr_read<v_rd_off(D0, 3, 1)>(vb);
;   asm volatile("s_waitcnt lgkmcnt(0)" ::: "memory"); SBAR();
;     ...
;   od = __builtin_amdgcn_mfma_f32_32x32x16_bf16(pa0, PK(l0, h0), od, 0, 0, 0);
;   od = __builtin_amdgcn_mfma_f32_32x32x16_bf16(pa1, PK(l1, h1), od, 0, 0, 0);
;   od = __builtin_amdgcn_mfma_f32_32x32x16_bf16(pa2, PK(l2, h2), od, 0, 0, 0);
;   od = __builtin_amdgcn_mfma_f32_32x32x16_bf16(pa3, PK(l3, h3), od, 0, 0, 0);
;     ...
; }
; __device__ __forceinline__ void pv_d0(f32x16* o, int vb, bf16x8 pa0, bf16x8 pa1, bf16x8 pa2, bf16x8 pa3) {
;   pv_one<0>(o[0], vb, pa0, pa1, pa2, pa3); pv_one<1>(o[1], vb, pa0, pa1, pa2, pa3); pv_one<2>(o[2], vb, pa0, pa1, pa2, pa3); pv_one<3>(o[3], vb, pa0, pa1, pa2, pa3);
.LBB0_147:
	v_max_f32_e32 v180, v97, v97
	v_max_f32_e32 v182, v96, v96
	v_max_f32_e32 v180, v182, v180
	v_max3_f32 v180, v180, v98, v99
	v_max3_f32 v180, v180, v100, v101
	v_max3_f32 v180, v180, v102, v103
	v_max3_f32 v180, v180, v104, v105
	v_max3_f32 v180, v180, v106, v107
	v_max3_f32 v180, v180, v108, v109
	v_max3_f32 v180, v180, v110, v111
	v_max3_f32 v180, v180, v80, v81
	v_max3_f32 v180, v180, v82, v83
	v_max3_f32 v180, v180, v84, v85
	v_max3_f32 v180, v180, v86, v87
	v_max3_f32 v180, v180, v88, v89
	v_max3_f32 v180, v180, v90, v91
	v_max3_f32 v180, v180, v92, v93
	v_max3_f32 v180, v180, v94, v95
	v_mov_b32_e32 v182, v180
	s_nop 1
	v_permlane32_swap_b32_e32 v180, v182
	v_max_f32_e32 v182, v182, v182
	v_max_f32_e32 v180, v180, v180
	v_max_f32_e32 v180, v180, v182
	s_nop 0
	s_waitcnt lgkmcnt(6)
	v_mfma_f32_32x32x16_bf16 v[0:15], v[64:67], v[210:213], v[0:15]
	ds_read_b64_tr_b16 v[210:211], v194 offset:0x200
	ds_read_b64_tr_b16 v[212:213], v194 offset:0xa00
	s_waitcnt lgkmcnt(6)
	v_mfma_f32_32x32x16_bf16 v[0:15], v[68:71], v[214:217], v[0:15]
	ds_read_b64_tr_b16 v[214:215], v194 offset:0x1200
	ds_read_b64_tr_b16 v[216:217], v194 offset:0x1a00
	s_waitcnt lgkmcnt(6)
	v_mfma_f32_32x32x16_bf16 v[0:15], v[72:75], v[218:221], v[0:15]
	ds_read_b64_tr_b16 v[218:219], v194 offset:0x2200
	ds_read_b64_tr_b16 v[220:221], v194 offset:0x2a00
	s_waitcnt lgkmcnt(6)
	v_mfma_f32_32x32x16_bf16 v[0:15], v[76:79], v[222:225], v[0:15]
	ds_read_b64_tr_b16 v[222:223], v194 offset:0x3200
	ds_read_b64_tr_b16 v[224:225], v194 offset:0x3a00
	s_waitcnt lgkmcnt(6)
	v_mfma_f32_32x32x16_bf16 v[48:63], v[64:67], v[210:213], v[48:63]
	ds_read_b64_tr_b16 v[210:211], v194 offset:0x400
	ds_read_b64_tr_b16 v[212:213], v194 offset:0xc00
	s_waitcnt lgkmcnt(6)
	v_mfma_f32_32x32x16_bf16 v[48:63], v[68:71], v[214:217], v[48:63]
	ds_read_b64_tr_b16 v[214:215], v194 offset:0x1400
	ds_read_b64_tr_b16 v[216:217], v194 offset:0x1c00
	s_waitcnt lgkmcnt(6)
	v_mfma_f32_32x32x16_bf16 v[48:63], v[72:75], v[218:221], v[48:63]
	ds_read_b64_tr_b16 v[218:219], v194 offset:0x2400
	ds_read_b64_tr_b16 v[220:221], v194 offset:0x2c00
	s_waitcnt lgkmcnt(6)
	v_mfma_f32_32x32x16_bf16 v[48:63], v[76:79], v[222:225], v[48:63]
	ds_read_b64_tr_b16 v[222:223], v194 offset:0x3400
	ds_read_b64_tr_b16 v[224:225], v194 offset:0x3c00
	s_waitcnt lgkmcnt(6)
	v_mfma_f32_32x32x16_bf16 v[32:47], v[64:67], v[210:213], v[32:47]
	ds_read_b64_tr_b16 v[210:211], v194 offset:0x600
	ds_read_b64_tr_b16 v[212:213], v194 offset:0xe00
	s_waitcnt lgkmcnt(6)
	v_mfma_f32_32x32x16_bf16 v[32:47], v[68:71], v[214:217], v[32:47]
	ds_read_b64_tr_b16 v[214:215], v194 offset:0x1600
	ds_read_b64_tr_b16 v[216:217], v194 offset:0x1e00
	s_waitcnt lgkmcnt(6)
	v_mfma_f32_32x32x16_bf16 v[32:47], v[72:75], v[218:221], v[32:47]
	ds_read_b64_tr_b16 v[218:219], v194 offset:0x2600
	ds_read_b64_tr_b16 v[220:221], v194 offset:0x2e00
	s_waitcnt lgkmcnt(6)
	v_mfma_f32_32x32x16_bf16 v[32:47], v[76:79], v[222:225], v[32:47]
	ds_read_b64_tr_b16 v[222:223], v194 offset:0x3600
	ds_read_b64_tr_b16 v[224:225], v194 offset:0x3e00
	s_waitcnt lgkmcnt(6)
	v_mfma_f32_32x32x16_bf16 v[16:31], v[64:67], v[210:213], v[16:31]
	s_waitcnt vmcnt(4)
	ds_write_b128 v195, v[150:153] offset:32768
	ds_write_b128 v196, v[146:149] offset:32768
	s_waitcnt lgkmcnt(6)
	v_mfma_f32_32x32x16_bf16 v[16:31], v[68:71], v[214:217], v[16:31]
	s_waitcnt lgkmcnt(4)
	v_mfma_f32_32x32x16_bf16 v[16:31], v[72:75], v[218:221], v[16:31]
	s_waitcnt lgkmcnt(2)
	v_mfma_f32_32x32x16_bf16 v[16:31], v[76:79], v[222:225], v[16:31]
	v_cmp_ge_f32_e32 vcc, s45, v180
	s_cmp_eq_u64 vcc, exec
	v_mov_b32_e32 v210, 1.0
	s_cbranch_scc0 .LBB0_164
.LBB0_148:
	v_exp_f32_e32 v226, v96
	v_exp_f32_e32 v244, v97
	v_exp_f32_e32 v224, v98
	v_exp_f32_e32 v227, v99
	v_exp_f32_e32 v223, v100
	v_exp_f32_e32 v225, v101
	v_exp_f32_e32 v221, v102
	v_exp_f32_e32 v222, v103
	v_exp_f32_e32 v218, v104
	v_exp_f32_e32 v220, v105
	v_exp_f32_e32 v217, v106
	v_exp_f32_e32 v219, v107
	v_exp_f32_e32 v214, v108
	v_exp_f32_e32 v216, v109
	v_exp_f32_e32 v213, v110
	v_exp_f32_e32 v215, v111
	s_waitcnt lgkmcnt(0)
	s_barrier
	s_waitcnt vmcnt(4)
	v_cmp_gt_f32_e32 vcc, 1.0, v210
	s_waitcnt vmcnt(4)
	ds_write_b128 v197, v[158:161]
	ds_write_b128 v198, v[154:157]
	s_cbranch_vccz .LBB0_152
	s_and_saveexec_b64 s[4:5], s[8:9]
	ds_write_b32 v190, v210 offset:128
	s_or_b64 exec, exec, s[4:5]
	s_waitcnt lgkmcnt(0)
	v_add_u32_e32 v76, v185, v112
	ds_read_b128 v[64:67], v76 offset:224
	ds_read_b128 v[68:71], v76 offset:192
	ds_read_b128 v[72:75], v76 offset:160
	ds_read_b128 v[76:79], v76 offset:128
	v_mov_b32_e32 v232, 0x80
	s_waitcnt lgkmcnt(3)
	v_pk_mul_f32 v[12:13], v[12:13], v[64:65]
	s_waitcnt lgkmcnt(2)
	v_pk_mul_f32 v[8:9], v[8:9], v[68:69]
	s_waitcnt lgkmcnt(1)
	v_pk_mul_f32 v[4:5], v[4:5], v[72:73]
	v_pk_mul_f32 v[14:15], v[14:15], v[66:67]
	v_pk_mul_f32 v[10:11], v[10:11], v[70:71]
	v_pk_mul_f32 v[6:7], v[6:7], v[74:75]
	s_waitcnt lgkmcnt(0)
	v_pk_mul_f32 v[2:3], v[2:3], v[78:79]
	v_pk_mul_f32 v[0:1], v[0:1], v[76:77]
	v_pk_mul_f32 v[60:61], v[60:61], v[64:65]
	v_pk_mul_f32 v[56:57], v[56:57], v[68:69]
	v_pk_mul_f32 v[52:53], v[52:53], v[72:73]
	v_pk_mul_f32 v[62:63], v[62:63], v[66:67]
	v_pk_mul_f32 v[58:59], v[58:59], v[70:71]
	v_pk_mul_f32 v[54:55], v[54:55], v[74:75]
	v_pk_mul_f32 v[50:51], v[50:51], v[78:79]
	v_pk_mul_f32 v[48:49], v[48:49], v[76:77]
	v_pk_mul_f32 v[44:45], v[44:45], v[64:65]
	v_pk_mul_f32 v[40:41], v[40:41], v[68:69]
	v_pk_mul_f32 v[36:37], v[36:37], v[72:73]
	v_pk_mul_f32 v[46:47], v[46:47], v[66:67]
	v_pk_mul_f32 v[42:43], v[42:43], v[70:71]
	v_pk_mul_f32 v[38:39], v[38:39], v[74:75]
	v_pk_mul_f32 v[34:35], v[34:35], v[78:79]
	v_pk_mul_f32 v[32:33], v[32:33], v[76:77]
	v_pk_mul_f32 v[28:29], v[28:29], v[64:65]
	v_pk_mul_f32 v[24:25], v[24:25], v[68:69]
	v_pk_mul_f32 v[20:21], v[20:21], v[72:73]
	v_pk_mul_f32 v[30:31], v[30:31], v[66:67]
	v_pk_mul_f32 v[26:27], v[26:27], v[70:71]
	v_pk_mul_f32 v[22:23], v[22:23], v[74:75]
	v_pk_mul_f32 v[18:19], v[18:19], v[78:79]
	v_pk_mul_f32 v[16:17], v[16:17], v[76:77]
	s_branch .LBB0_153

; #define SBAR() __builtin_amdgcn_sched_barrier(0)
; #define SLOAD_A(k0) do { vs0a = *reinterpret_cast<const bf16x8*>(&Vh[(long)((k0) + sr) * LDK + sc]); vs1a = *reinterpret_cast<const bf16x8*>(&Vh[(long)((k0) + 32 + sr) * LDK + sc]); KLOAD(ks0a, ks1a, k0); } while (0)
; __device__ __forceinline__ void finishSM(f32x16& p0, f32x16& p1, float alpha, float& l_reg, bf16x8& pa0, bf16x8& pa1, bf16x8& pa2, bf16x8& pa3) {
; #pragma unroll
;   for (int r = 0; r < 16; ++r) p1[r] = __builtin_amdgcn_exp2f(p1[r]);
;   float ps = 0;
; #pragma unroll
;   for (int r = 0; r < 16; ++r) ps += p0[r];
; #pragma unroll
;   for (int r = 0; r < 16; ++r) ps += p1[r];
;   { auto rr = __builtin_amdgcn_permlane32_swap(__float_as_uint(ps), __float_as_uint(ps), false, false);
;     ps = __uint_as_float(rr[0]) + __uint_as_float(rr[1]); }
;   l_reg = l_reg * alpha + ps;
;     ...
;   PK4(p0, 0, pa0); PK4(p0, 8, pa1); PK4(p1, 0, pa2); PK4(p1, 8, pa3);
; template <int ND0, int LDQ, int LDK, int LDO> ...
;     ...
;     SBAR(); qkt<ND0>(pA0, pA1, Kq0, qr, r32, hi);
;     finishSM(pB0, pB1, alB, l_reg, pa0, pa1, pa2, pa3); SBAR();
;     if (j + 3 < NT) SLOAD_A((j + 3) * KVBLK); SBAR();
.LBB0_153:
	v_mov_b32_e32 v242, 0x800
	ds_read_b128 v[64:67], v199 offset:32768
	ds_read_b128 v[68:71], v199 offset:40960
	ds_read_b128 v[238:241], v200 offset:32768
	ds_read_b128 v[234:237], v200 offset:40960
	v_exp_f32_e32 v245, v88
	v_exp_f32_e32 v246, v89
	s_waitcnt lgkmcnt(3)
	v_mfma_f32_32x32x16_bf16 v[96:111], v[64:67], v[114:117], 0
	v_exp_f32_e32 v247, v90
	v_exp_f32_e32 v231, v91
	v_exp_f32_e32 v243, v92
	v_exp_f32_e32 v252, v93
	v_exp_f32_e32 v253, v94
	v_exp_f32_e32 v95, v95
	s_waitcnt lgkmcnt(2)
	v_mfma_f32_32x32x16_bf16 v[64:79], v[68:71], v[114:117], 0
	s_waitcnt lgkmcnt(1)
	v_mfma_f32_32x32x16_bf16 v[96:111], v[238:241], v[122:125], v[96:111]
	s_waitcnt lgkmcnt(0)
	v_mfma_f32_32x32x16_bf16 v[64:79], v[234:237], v[122:125], v[64:79]
	ds_read_b128 v[234:237], v202 offset:32768
	ds_read_b128 v[238:241], v202 offset:40960
	s_waitcnt lgkmcnt(1)
	v_mfma_f32_32x32x16_bf16 v[96:111], v[234:237], v[142:145], v[96:111]
	s_waitcnt lgkmcnt(0)
	v_mfma_f32_32x32x16_bf16 v[64:79], v[238:241], v[142:145], v[64:79]
	ds_read_b128 v[234:237], v201 offset:32768
	ds_read_b128 v[238:241], v201 offset:40960
	s_waitcnt lgkmcnt(1)
	v_mfma_f32_32x32x16_bf16 v[96:111], v[234:237], v[138:141], v[96:111]
	s_waitcnt lgkmcnt(0)
	v_mfma_f32_32x32x16_bf16 v[64:79], v[238:241], v[138:141], v[64:79]
	ds_read_b128 v[234:237], v203 offset:32768
	ds_read_b128 v[238:241], v203 offset:40960
	s_waitcnt lgkmcnt(1)
	v_mfma_f32_32x32x16_bf16 v[96:111], v[234:237], v[134:137], v[96:111]
	s_waitcnt lgkmcnt(0)
	v_mfma_f32_32x32x16_bf16 v[64:79], v[238:241], v[134:137], v[64:79]
	ds_read_b128 v[234:237], v204 offset:32768
	ds_read_b128 v[238:241], v204 offset:40960
	s_waitcnt lgkmcnt(1)
	v_mfma_f32_32x32x16_bf16 v[96:111], v[234:237], v[130:133], v[96:111]
	s_waitcnt lgkmcnt(0)
	v_mfma_f32_32x32x16_bf16 v[64:79], v[238:241], v[130:133], v[64:79]
	ds_read_b128 v[234:237], v206 offset:32768
	ds_read_b128 v[238:241], v206 offset:40960
	s_waitcnt lgkmcnt(1)
	v_mfma_f32_32x32x16_bf16 v[96:111], v[234:237], v[126:129], v[96:111]
	s_waitcnt lgkmcnt(0)
	v_mfma_f32_32x32x16_bf16 v[64:79], v[238:241], v[126:129], v[64:79]
	ds_read_b128 v[234:237], v205 offset:32768
	ds_read_b128 v[238:241], v205 offset:40960
	s_waitcnt lgkmcnt(1)
	v_mfma_f32_32x32x16_bf16 v[96:111], v[234:237], v[118:121], v[96:111]
	v_exp_f32_e32 v234, v80
	v_add_f32_e32 v80, 0, v226
	v_add_f32_e32 v80, v244, v80
	v_add_f32_e32 v80, v224, v80
	v_add_f32_e32 v80, v227, v80
	v_add_f32_e32 v80, v223, v80
	v_add_f32_e32 v80, v225, v80
	v_add_f32_e32 v80, v221, v80
	v_add_f32_e32 v80, v222, v80
	v_add_f32_e32 v80, v218, v80
	v_add_f32_e32 v80, v220, v80
	v_add_f32_e32 v80, v217, v80
	v_add_f32_e32 v80, v219, v80
	v_add_f32_e32 v80, v214, v80
	v_exp_f32_e32 v235, v81
	v_add_f32_e32 v80, v216, v80
	v_exp_f32_e32 v236, v82
	v_add_f32_e32 v80, v213, v80
	v_exp_f32_e32 v237, v83
	v_add_f32_e32 v80, v215, v80
	s_waitcnt lgkmcnt(0)
	v_mfma_f32_32x32x16_bf16 v[64:79], v[238:241], v[118:121], v[64:79]
	v_exp_f32_e32 v238, v84
	v_add_f32_e32 v80, v234, v80
	v_exp_f32_e32 v239, v85
	v_add_f32_e32 v80, v235, v80
	v_exp_f32_e32 v240, v86
	v_add_f32_e32 v80, v236, v80
	v_exp_f32_e32 v241, v87
	v_add_f32_e32 v80, v237, v80
	v_add_f32_e32 v80, v238, v80
	v_add_f32_e32 v80, v239, v80
	v_add_f32_e32 v80, v240, v80
	v_add_f32_e32 v80, v241, v80
	v_add_f32_e32 v80, v245, v80
	v_add_f32_e32 v80, v246, v80
	v_add_f32_e32 v80, v247, v80
	v_add_f32_e32 v80, v231, v80
	v_add_f32_e32 v80, v243, v80
	v_add_f32_e32 v80, v252, v80
	v_add_f32_e32 v80, v253, v80
	v_add_f32_e32 v211, v95, v80
	v_mov_b32_e32 v212, v211
	v_cvt_pk_bf16_f32 v80, v226, v244
	v_cvt_pk_bf16_f32 v81, v224, v227
	v_cvt_pk_bf16_f32 v82, v223, v225
	v_cvt_pk_bf16_f32 v83, v221, v222
	v_cvt_pk_bf16_f32 v84, v218, v220
	v_cvt_pk_bf16_f32 v85, v217, v219
	v_cvt_pk_bf16_f32 v86, v214, v216
	v_cvt_pk_bf16_f32 v87, v213, v215
	v_cvt_pk_bf16_f32 v88, v234, v235
	v_cvt_pk_bf16_f32 v89, v236, v237
	v_cvt_pk_bf16_f32 v90, v238, v239
	v_cvt_pk_bf16_f32 v91, v240, v241
	v_cvt_pk_bf16_f32 v92, v245, v246
	v_cvt_pk_bf16_f32 v93, v247, v231
	v_cvt_pk_bf16_f32 v94, v243, v252
	v_cvt_pk_bf16_f32 v95, v253, v95
	s_nop 1
	v_permlane32_swap_b32_e32 v211, v212
	v_permlane32_swap_b32_e32 v80, v82
	v_permlane32_swap_b32_e32 v81, v83
	v_permlane32_swap_b32_e32 v84, v86
	v_permlane32_swap_b32_e32 v85, v87
	v_permlane32_swap_b32_e32 v88, v90
	v_permlane32_swap_b32_e32 v89, v91
	v_permlane32_swap_b32_e32 v92, v94
	v_permlane32_swap_b32_e32 v93, v95
	s_add_i32 s39, s39, 2
	s_cmp_ge_u32 s39, s38
	s_cselect_b64 s[4:5], -1, 0
	s_and_b64 vcc, exec, s[4:5]
	s_cbranch_vccnz .Lgqa_pf_skip
	v_add_co_u32_e32 v146, vcc, 0xfffe8000, v188
	s_nop 1
	v_addc_co_u32_e32 v147, vcc, -1, v189, vcc
	global_load_dwordx4 v[158:161], v[146:147], off
	global_load_dwordx4 v[150:153], v[146:147], off offset:-512
	global_load_dwordx4 v[154:157], v[188:189], off
	s_nop 0
	global_load_dwordx4 v[146:149], v[188:189], off offset:-512

; #define SBAR() __builtin_amdgcn_sched_barrier(0)
; template <int OFF> __device__ __forceinline__ s16x4 tr_read(int vb) {
;   s16x4 r; asm volatile("ds_read_b64_tr_b16 %0, %1 offset:%2" : "=&v"(r) : "v"(vb), "i"(OFF) : "memory"); return r;
; }
; template <int D0> __device__ __forceinline__ void pv_one(f32x16& od, int vb, bf16x8 pa0, bf16x8 pa1, bf16x8 pa2, bf16x8 pa3) {
;   const s16x4 l0 = tr_read<v_rd_off(D0, 0, 0)>(vb), h0 = tr_read<v_rd_off(D0, 0, 1)>(vb), l1 = tr_read<v_rd_off(D0, 1, 0)>(vb), h1 = tr_read<v_rd_off(D0, 1, 1)>(vb);
;   const s16x4 l2 = tr_read<v_rd_off(D0, 2, 0)>(vb), h2 = tr_read<v_rd_off(D0, 2, 1)>(vb), l3 = tr_read<v_rd_off(D0, 3, 0)>(vb), h3 = tr_read<v_rd_off(D0, 3, 1)>(vb);
;   asm volatile("s_waitcnt lgkmcnt(0)" ::: "memory"); SBAR();
;     ...
;   od = __builtin_amdgcn_mfma_f32_32x32x16_bf16(pa0, PK(l0, h0), od, 0, 0, 0);
;   od = __builtin_amdgcn_mfma_f32_32x32x16_bf16(pa1, PK(l1, h1), od, 0, 0, 0);
;   od = __builtin_amdgcn_mfma_f32_32x32x16_bf16(pa2, PK(l2, h2), od, 0, 0, 0);
;   od = __builtin_amdgcn_mfma_f32_32x32x16_bf16(pa3, PK(l3, h3), od, 0, 0, 0);
;     ...
; }
; __device__ __forceinline__ void pv_d0(f32x16* o, int vb, bf16x8 pa0, bf16x8 pa1, bf16x8 pa2, bf16x8 pa3) {
;   pv_one<0>(o[0], vb, pa0, pa1, pa2, pa3); pv_one<1>(o[1], vb, pa0, pa1, pa2, pa3); pv_one<2>(o[2], vb, pa0, pa1, pa2, pa3); pv_one<3>(o[3], vb, pa0, pa1, pa2, pa3);
.LBB0_156:
	v_max_f32_e32 v180, v97, v97
	v_max_f32_e32 v182, v96, v96
	v_max_f32_e32 v180, v182, v180
	v_max3_f32 v180, v180, v98, v99
	v_max3_f32 v180, v180, v100, v101
	v_max3_f32 v180, v180, v102, v103
	v_max3_f32 v180, v180, v104, v105
	v_max3_f32 v180, v180, v106, v107
	v_max3_f32 v180, v180, v108, v109
	v_max3_f32 v180, v180, v110, v111
	v_max3_f32 v180, v180, v64, v65
	v_max3_f32 v180, v180, v66, v67
	v_max3_f32 v180, v180, v68, v69
	v_max3_f32 v180, v180, v70, v71
	v_max3_f32 v180, v180, v72, v73
	v_max3_f32 v180, v180, v74, v75
	v_max3_f32 v180, v180, v76, v77
	v_max3_f32 v180, v180, v78, v79
	v_mov_b32_e32 v182, v180
	s_nop 1
	v_permlane32_swap_b32_e32 v180, v182
	v_max_f32_e32 v182, v182, v182
	v_max_f32_e32 v180, v180, v180
	v_max_f32_e32 v180, v180, v182
	s_nop 0
	s_waitcnt lgkmcnt(6)
	v_mfma_f32_32x32x16_bf16 v[0:15], v[80:83], v[214:217], v[0:15]
	ds_read_b64_tr_b16 v[214:215], v191 offset:0x200
	ds_read_b64_tr_b16 v[216:217], v191 offset:0xa00
	s_waitcnt lgkmcnt(6)
	v_mfma_f32_32x32x16_bf16 v[0:15], v[84:87], v[218:221], v[0:15]
	ds_read_b64_tr_b16 v[218:219], v191 offset:0x1200
	ds_read_b64_tr_b16 v[220:221], v191 offset:0x1a00
	s_waitcnt lgkmcnt(6)
	v_mfma_f32_32x32x16_bf16 v[0:15], v[88:91], v[222:225], v[0:15]
	ds_read_b64_tr_b16 v[222:223], v191 offset:0x2200
	ds_read_b64_tr_b16 v[224:225], v191 offset:0x2a00
	s_waitcnt lgkmcnt(6)
	v_mfma_f32_32x32x16_bf16 v[0:15], v[92:95], v[234:237], v[0:15]
	ds_read_b64_tr_b16 v[234:235], v191 offset:0x3200
	ds_read_b64_tr_b16 v[236:237], v191 offset:0x3a00
	s_waitcnt lgkmcnt(6)
	v_mfma_f32_32x32x16_bf16 v[48:63], v[80:83], v[214:217], v[48:63]
	ds_read_b64_tr_b16 v[214:215], v191 offset:0x400
	ds_read_b64_tr_b16 v[216:217], v191 offset:0xc00
	s_waitcnt lgkmcnt(6)
	v_mfma_f32_32x32x16_bf16 v[48:63], v[84:87], v[218:221], v[48:63]
	ds_read_b64_tr_b16 v[218:219], v191 offset:0x1400
	ds_read_b64_tr_b16 v[220:221], v191 offset:0x1c00
	s_waitcnt lgkmcnt(6)
	v_mfma_f32_32x32x16_bf16 v[48:63], v[88:91], v[222:225], v[48:63]
	ds_read_b64_tr_b16 v[222:223], v191 offset:0x2400
	ds_read_b64_tr_b16 v[224:225], v191 offset:0x2c00
	s_waitcnt lgkmcnt(6)
	v_mfma_f32_32x32x16_bf16 v[48:63], v[92:95], v[234:237], v[48:63]
	ds_read_b64_tr_b16 v[234:235], v191 offset:0x3400
	ds_read_b64_tr_b16 v[236:237], v191 offset:0x3c00
	s_waitcnt lgkmcnt(6)
	v_mfma_f32_32x32x16_bf16 v[32:47], v[80:83], v[214:217], v[32:47]
	ds_read_b64_tr_b16 v[214:215], v191 offset:0x600
	ds_read_b64_tr_b16 v[216:217], v191 offset:0xe00
	s_waitcnt lgkmcnt(6)
	v_mfma_f32_32x32x16_bf16 v[32:47], v[84:87], v[218:221], v[32:47]
	ds_read_b64_tr_b16 v[218:219], v191 offset:0x1600
	ds_read_b64_tr_b16 v[220:221], v191 offset:0x1e00
	s_waitcnt lgkmcnt(6)
	v_mfma_f32_32x32x16_bf16 v[32:47], v[88:91], v[222:225], v[32:47]
	ds_read_b64_tr_b16 v[222:223], v191 offset:0x2600
	ds_read_b64_tr_b16 v[224:225], v191 offset:0x2e00
	s_waitcnt lgkmcnt(6)
	v_mfma_f32_32x32x16_bf16 v[32:47], v[92:95], v[234:237], v[32:47]
	ds_read_b64_tr_b16 v[234:235], v191 offset:0x3600
	ds_read_b64_tr_b16 v[236:237], v191 offset:0x3e00
	s_waitcnt lgkmcnt(6)
	v_mfma_f32_32x32x16_bf16 v[16:31], v[80:83], v[214:217], v[16:31]
	s_waitcnt vmcnt(4)
	ds_write_b128 v195, v[170:173] offset:49152
	ds_write_b128 v196, v[174:177] offset:49152
	s_waitcnt lgkmcnt(6)
	v_mfma_f32_32x32x16_bf16 v[16:31], v[84:87], v[218:221], v[16:31]
	s_waitcnt lgkmcnt(4)
	v_mfma_f32_32x32x16_bf16 v[16:31], v[88:91], v[222:225], v[16:31]
	s_waitcnt lgkmcnt(2)
	v_mfma_f32_32x32x16_bf16 v[16:31], v[92:95], v[234:237], v[16:31]
	v_cmp_ge_f32_e32 vcc, s45, v180
	s_cmp_eq_u64 vcc, exec
	v_mov_b32_e32 v170, 1.0
	s_cbranch_scc0 .LBB0_166
.LBB0_157:
	v_exp_f32_e32 v176, v96
	v_exp_f32_e32 v213, v97
	v_exp_f32_e32 v174, v98
	v_exp_f32_e32 v177, v99
	v_exp_f32_e32 v173, v100
	v_exp_f32_e32 v175, v101
	v_exp_f32_e32 v171, v102
	v_exp_f32_e32 v172, v103
	s_waitcnt lgkmcnt(0)
	s_barrier
	s_waitcnt vmcnt(4)
	v_cmp_gt_f32_e32 vcc, 1.0, v170
	ds_write_b128 v197, v[162:165] offset:16384
	ds_write_b128 v198, v[166:169] offset:16384
	s_cbranch_vccz .LBB0_161
	s_and_saveexec_b64 s[16:17], s[8:9]
	ds_write_b32 v190, v170 offset:128
	s_or_b64 exec, exec, s[16:17]
	s_waitcnt lgkmcnt(0)
	v_add_u32_e32 v92, v185, v112
	ds_read_b128 v[80:83], v92 offset:224
	ds_read_b128 v[84:87], v92 offset:192
	ds_read_b128 v[88:91], v92 offset:160
	ds_read_b128 v[92:95], v92 offset:128
	s_waitcnt lgkmcnt(3)
	v_pk_mul_f32 v[12:13], v[12:13], v[80:81]
	s_waitcnt lgkmcnt(2)
	v_pk_mul_f32 v[8:9], v[8:9], v[84:85]
	s_waitcnt lgkmcnt(1)
	v_pk_mul_f32 v[4:5], v[4:5], v[88:89]
	v_pk_mul_f32 v[14:15], v[14:15], v[82:83]
	v_pk_mul_f32 v[10:11], v[10:11], v[86:87]
	v_pk_mul_f32 v[6:7], v[6:7], v[90:91]
	s_waitcnt lgkmcnt(0)
	v_pk_mul_f32 v[2:3], v[2:3], v[94:95]
	v_pk_mul_f32 v[0:1], v[0:1], v[92:93]
	v_pk_mul_f32 v[60:61], v[60:61], v[80:81]
	v_pk_mul_f32 v[56:57], v[56:57], v[84:85]
	v_pk_mul_f32 v[52:53], v[52:53], v[88:89]
	v_pk_mul_f32 v[62:63], v[62:63], v[82:83]
	v_pk_mul_f32 v[58:59], v[58:59], v[86:87]
	v_pk_mul_f32 v[54:55], v[54:55], v[90:91]
	v_pk_mul_f32 v[50:51], v[50:51], v[94:95]
	v_pk_mul_f32 v[48:49], v[48:49], v[92:93]
	v_pk_mul_f32 v[44:45], v[44:45], v[80:81]
	v_pk_mul_f32 v[40:41], v[40:41], v[84:85]
	v_pk_mul_f32 v[36:37], v[36:37], v[88:89]
	v_pk_mul_f32 v[46:47], v[46:47], v[82:83]
	v_pk_mul_f32 v[42:43], v[42:43], v[86:87]
	v_pk_mul_f32 v[38:39], v[38:39], v[90:91]
	v_pk_mul_f32 v[34:35], v[34:35], v[94:95]
	v_pk_mul_f32 v[32:33], v[32:33], v[92:93]
	v_pk_mul_f32 v[28:29], v[28:29], v[80:81]
	v_pk_mul_f32 v[24:25], v[24:25], v[84:85]
	v_pk_mul_f32 v[20:21], v[20:21], v[88:89]
	v_pk_mul_f32 v[30:31], v[30:31], v[82:83]
	v_pk_mul_f32 v[26:27], v[26:27], v[86:87]
	v_pk_mul_f32 v[22:23], v[22:23], v[90:91]
	v_pk_mul_f32 v[18:19], v[18:19], v[94:95]
	v_pk_mul_f32 v[16:17], v[16:17], v[92:93]
.LBB0_161:
	v_add_f32_e32 v80, v208, v209
	v_fmac_f32_e32 v80, v207, v192
	v_add_f32_e32 v192, v211, v212
	v_fmac_f32_e32 v192, v80, v210
	ds_read_b128 v[80:83], v199 offset:49152
	ds_read_b128 v[84:87], v199 offset:57344
	v_exp_f32_e32 v167, v104
	v_exp_f32_e32 v169, v105
	v_exp_f32_e32 v166, v106
	v_exp_f32_e32 v168, v107
	v_exp_f32_e32 v163, v108
	v_exp_f32_e32 v165, v109
	v_exp_f32_e32 v162, v110
	v_exp_f32_e32 v164, v111
	v_lshl_add_u64 v[188:189], v[188:189], 0, s[42:43]
	s_and_b64 vcc, exec, s[4:5]
	s_cbranch_vccnz .LBB0_167
	v_mov_b32_e32 v207, v170
	s_branch .LBB0_146

; #define SBAR() __builtin_amdgcn_sched_barrier(0)
; template <int OFF> __device__ __forceinline__ s16x4 tr_read(int vb) {
;   s16x4 r; asm volatile("ds_read_b64_tr_b16 %0, %1 offset:%2" : "=&v"(r) : "v"(vb), "i"(OFF) : "memory"); return r;
; }
; template <int D0> __device__ __forceinline__ void pv_one(f32x16& od, int vb, bf16x8 pa0, bf16x8 pa1, bf16x8 pa2, bf16x8 pa3) {
;   const s16x4 l0 = tr_read<v_rd_off(D0, 0, 0)>(vb), h0 = tr_read<v_rd_off(D0, 0, 1)>(vb), l1 = tr_read<v_rd_off(D0, 1, 0)>(vb), h1 = tr_read<v_rd_off(D0, 1, 1)>(vb);
;   const s16x4 l2 = tr_read<v_rd_off(D0, 2, 0)>(vb), h2 = tr_read<v_rd_off(D0, 2, 1)>(vb), l3 = tr_read<v_rd_off(D0, 3, 0)>(vb), h3 = tr_read<v_rd_off(D0, 3, 1)>(vb);
;   asm volatile("s_waitcnt lgkmcnt(0)" ::: "memory"); SBAR();
;     ...
;   od = __builtin_amdgcn_mfma_f32_32x32x16_bf16(pa0, PK(l0, h0), od, 0, 0, 0);
;   od = __builtin_amdgcn_mfma_f32_32x32x16_bf16(pa1, PK(l1, h1), od, 0, 0, 0);
;   od = __builtin_amdgcn_mfma_f32_32x32x16_bf16(pa2, PK(l2, h2), od, 0, 0, 0);
;   od = __builtin_amdgcn_mfma_f32_32x32x16_bf16(pa3, PK(l3, h3), od, 0, 0, 0);
;     ...
; }
; __device__ __forceinline__ void pv_d0(f32x16* o, int vb, bf16x8 pa0, bf16x8 pa1, bf16x8 pa2, bf16x8 pa3) {
;   pv_one<0>(o[0], vb, pa0, pa1, pa2, pa3); pv_one<1>(o[1], vb, pa0, pa1, pa2, pa3); pv_one<2>(o[2], vb, pa0, pa1, pa2, pa3); pv_one<3>(o[3], vb, pa0, pa1, pa2, pa3);
.LBB0_215:
	v_max_f32_e32 v252, v97, v97
	v_max_f32_e32 v253, v96, v96
	v_max_f32_e32 v252, v253, v252
	v_max3_f32 v252, v252, v98, v99
	v_max3_f32 v252, v252, v100, v101
	v_max3_f32 v252, v252, v102, v103
	v_max3_f32 v252, v252, v104, v105
	v_max3_f32 v252, v252, v106, v107
	v_max3_f32 v252, v252, v108, v109
	v_max3_f32 v252, v252, v110, v111
	v_max3_f32 v252, v252, v80, v81
	v_max3_f32 v252, v252, v82, v83
	v_max3_f32 v252, v252, v84, v85
	v_max3_f32 v252, v252, v86, v87
	v_max3_f32 v252, v252, v88, v89
	v_max3_f32 v252, v252, v90, v91
	v_max3_f32 v252, v252, v92, v93
	v_max3_f32 v252, v252, v94, v95
	v_mov_b32_e32 v253, v252
	s_nop 1
	v_permlane32_swap_b32_e32 v252, v253
	v_max_f32_e32 v253, v253, v253
	v_max_f32_e32 v252, v252, v252
	v_max_f32_e32 v252, v252, v253
	s_nop 0
	s_waitcnt lgkmcnt(6)
	v_mfma_f32_32x32x16_bf16 v[0:15], v[64:67], v[204:207], v[0:15]
	ds_read_b64_tr_b16 v[204:205], v192 offset:0x200
	ds_read_b64_tr_b16 v[206:207], v192 offset:0xa00
	s_waitcnt lgkmcnt(6)
	v_mfma_f32_32x32x16_bf16 v[0:15], v[68:71], v[208:211], v[0:15]
	ds_read_b64_tr_b16 v[208:209], v192 offset:0x1200
	ds_read_b64_tr_b16 v[210:211], v192 offset:0x1a00
	s_waitcnt lgkmcnt(6)
	v_mfma_f32_32x32x16_bf16 v[0:15], v[72:75], v[212:215], v[0:15]
	ds_read_b64_tr_b16 v[212:213], v192 offset:0x2200
	ds_read_b64_tr_b16 v[214:215], v192 offset:0x2a00
	s_waitcnt lgkmcnt(6)
	v_mfma_f32_32x32x16_bf16 v[0:15], v[76:79], v[216:219], v[0:15]
	ds_read_b64_tr_b16 v[216:217], v192 offset:0x3200
	ds_read_b64_tr_b16 v[218:219], v192 offset:0x3a00
	s_waitcnt lgkmcnt(6)
	v_mfma_f32_32x32x16_bf16 v[48:63], v[64:67], v[204:207], v[48:63]
	ds_read_b64_tr_b16 v[204:205], v192 offset:0x400
	ds_read_b64_tr_b16 v[206:207], v192 offset:0xc00
	s_waitcnt lgkmcnt(6)
	v_mfma_f32_32x32x16_bf16 v[48:63], v[68:71], v[208:211], v[48:63]
	ds_read_b64_tr_b16 v[208:209], v192 offset:0x1400
	ds_read_b64_tr_b16 v[210:211], v192 offset:0x1c00
	s_waitcnt lgkmcnt(6)
	v_mfma_f32_32x32x16_bf16 v[48:63], v[72:75], v[212:215], v[48:63]
	ds_read_b64_tr_b16 v[212:213], v192 offset:0x2400
	ds_read_b64_tr_b16 v[214:215], v192 offset:0x2c00
	s_waitcnt lgkmcnt(6)
	v_mfma_f32_32x32x16_bf16 v[48:63], v[76:79], v[216:219], v[48:63]
	ds_read_b64_tr_b16 v[216:217], v192 offset:0x3400
	ds_read_b64_tr_b16 v[218:219], v192 offset:0x3c00
	s_waitcnt lgkmcnt(6)
	v_mfma_f32_32x32x16_bf16 v[32:47], v[64:67], v[204:207], v[32:47]
	ds_read_b64_tr_b16 v[204:205], v192 offset:0x600
	ds_read_b64_tr_b16 v[206:207], v192 offset:0xe00
	s_waitcnt lgkmcnt(6)
	v_mfma_f32_32x32x16_bf16 v[32:47], v[68:71], v[208:211], v[32:47]
	ds_read_b64_tr_b16 v[208:209], v192 offset:0x1600
	ds_read_b64_tr_b16 v[210:211], v192 offset:0x1e00
	s_waitcnt lgkmcnt(6)
	v_mfma_f32_32x32x16_bf16 v[32:47], v[72:75], v[212:215], v[32:47]
	ds_read_b64_tr_b16 v[212:213], v192 offset:0x2600
	ds_read_b64_tr_b16 v[214:215], v192 offset:0x2e00
	s_waitcnt lgkmcnt(6)
	v_mfma_f32_32x32x16_bf16 v[32:47], v[76:79], v[216:219], v[32:47]
	ds_read_b64_tr_b16 v[216:217], v192 offset:0x3600
	ds_read_b64_tr_b16 v[218:219], v192 offset:0x3e00
	s_waitcnt lgkmcnt(6)
	v_mfma_f32_32x32x16_bf16 v[16:31], v[64:67], v[204:207], v[16:31]
	s_waitcnt vmcnt(3)
	ds_write_b128 v195, v[138:141] offset:32768
	s_waitcnt lgkmcnt(5)
	v_mfma_f32_32x32x16_bf16 v[16:31], v[68:71], v[208:211], v[16:31]
	s_waitcnt lgkmcnt(3)
	v_mfma_f32_32x32x16_bf16 v[16:31], v[72:75], v[212:215], v[16:31]
	s_waitcnt lgkmcnt(1)
	v_mfma_f32_32x32x16_bf16 v[16:31], v[76:79], v[216:219], v[16:31]
	v_cmp_ge_f32_e32 vcc, s45, v252
	s_cmp_eq_u64 vcc, exec
	v_mov_b32_e32 v203, 1.0
	s_cbranch_scc0 .LBB0_231
.LBB0_216:
	v_exp_f32_e32 v219, v96
	v_exp_f32_e32 v221, v97
	v_exp_f32_e32 v217, v98
	v_exp_f32_e32 v220, v99
	v_exp_f32_e32 v215, v100
	v_exp_f32_e32 v218, v101
	v_exp_f32_e32 v214, v102
	v_exp_f32_e32 v216, v103
	v_exp_f32_e32 v211, v104
	v_exp_f32_e32 v213, v105
	v_exp_f32_e32 v209, v106
	v_exp_f32_e32 v212, v107
	v_exp_f32_e32 v207, v108
	v_exp_f32_e32 v210, v109
	v_exp_f32_e32 v206, v110
	v_exp_f32_e32 v208, v111
	s_waitcnt lgkmcnt(0)
	s_barrier
	s_waitcnt vmcnt(3)
	v_cmp_gt_f32_e32 vcc, 1.0, v203
	s_waitcnt vmcnt(3)
	ds_write_b128 v193, v[130:133]
	ds_write_b128 v194, v[134:137]
	s_cbranch_vccz .LBB0_220
	s_and_saveexec_b64 s[18:19], s[6:7]
	ds_write_b32 v187, v203 offset:128
	s_or_b64 exec, exec, s[18:19]
	s_waitcnt lgkmcnt(0)
	v_add_u32_e32 v76, v161, v112
	ds_read_b128 v[64:67], v76 offset:224
	ds_read_b128 v[68:71], v76 offset:192
	ds_read_b128 v[72:75], v76 offset:160
	ds_read_b128 v[76:79], v76 offset:128
	s_waitcnt lgkmcnt(3)
	v_pk_mul_f32 v[12:13], v[12:13], v[64:65]
	s_waitcnt lgkmcnt(2)
	v_pk_mul_f32 v[8:9], v[8:9], v[68:69]
	s_waitcnt lgkmcnt(1)
	v_pk_mul_f32 v[4:5], v[4:5], v[72:73]
	v_pk_mul_f32 v[14:15], v[14:15], v[66:67]
	v_pk_mul_f32 v[10:11], v[10:11], v[70:71]
	v_pk_mul_f32 v[6:7], v[6:7], v[74:75]
	s_waitcnt lgkmcnt(0)
	v_pk_mul_f32 v[2:3], v[2:3], v[78:79]
	v_pk_mul_f32 v[0:1], v[0:1], v[76:77]
	v_pk_mul_f32 v[60:61], v[60:61], v[64:65]
	v_pk_mul_f32 v[56:57], v[56:57], v[68:69]
	v_pk_mul_f32 v[52:53], v[52:53], v[72:73]
	v_pk_mul_f32 v[62:63], v[62:63], v[66:67]
	v_pk_mul_f32 v[58:59], v[58:59], v[70:71]
	v_pk_mul_f32 v[54:55], v[54:55], v[74:75]
	v_pk_mul_f32 v[50:51], v[50:51], v[78:79]
	v_pk_mul_f32 v[48:49], v[48:49], v[76:77]
	v_pk_mul_f32 v[44:45], v[44:45], v[64:65]
	v_pk_mul_f32 v[40:41], v[40:41], v[68:69]
	v_pk_mul_f32 v[36:37], v[36:37], v[72:73]
	v_pk_mul_f32 v[46:47], v[46:47], v[66:67]
	v_pk_mul_f32 v[42:43], v[42:43], v[70:71]
	v_pk_mul_f32 v[38:39], v[38:39], v[74:75]
	v_pk_mul_f32 v[34:35], v[34:35], v[78:79]
	v_pk_mul_f32 v[32:33], v[32:33], v[76:77]
	v_pk_mul_f32 v[28:29], v[28:29], v[64:65]
	v_pk_mul_f32 v[24:25], v[24:25], v[68:69]
	v_pk_mul_f32 v[20:21], v[20:21], v[72:73]
	v_pk_mul_f32 v[30:31], v[30:31], v[66:67]
	v_pk_mul_f32 v[26:27], v[26:27], v[70:71]
	v_pk_mul_f32 v[22:23], v[22:23], v[74:75]
	v_pk_mul_f32 v[18:19], v[18:19], v[78:79]
	v_pk_mul_f32 v[16:17], v[16:17], v[76:77]
; #define SBAR() __builtin_amdgcn_sched_barrier(0)
; #define SLOAD_A(k0) do { vs0a = *reinterpret_cast<const bf16x8*>(&Vh[(long)((k0) + sr) * LDK + sc]); vs1a = *reinterpret_cast<const bf16x8*>(&Vh[(long)((k0) + 32 + sr) * LDK + sc]); KLOAD(ks0a, ks1a, k0); } while (0)
; __device__ __forceinline__ void finishSM(f32x16& p0, f32x16& p1, float alpha, float& l_reg, bf16x8& pa0, bf16x8& pa1, bf16x8& pa2, bf16x8& pa3) {
; #pragma unroll
;   for (int r = 0; r < 16; ++r) p1[r] = __builtin_amdgcn_exp2f(p1[r]);
;   float ps = 0;
; #pragma unroll
;   for (int r = 0; r < 16; ++r) ps += p0[r];
; #pragma unroll
;   for (int r = 0; r < 16; ++r) ps += p1[r];
;   { auto rr = __builtin_amdgcn_permlane32_swap(__float_as_uint(ps), __float_as_uint(ps), false, false);
;     ps = __uint_as_float(rr[0]) + __uint_as_float(rr[1]); }
;   l_reg = l_reg * alpha + ps;
;     ...
;   PK4(p0, 0, pa0); PK4(p0, 8, pa1); PK4(p1, 0, pa2); PK4(p1, 8, pa3);
; template <int ND0, int LDQ, int LDK, int LDO> ...
;     ...
;     SBAR(); qkt<ND0>(pA0, pA1, Kq0, qr, r32, hi);
;     finishSM(pB0, pB1, alB, l_reg, pa0, pa1, pa2, pa3); SBAR();
;     if (j + 3 < NT) SLOAD_A((j + 3) * KVBLK); SBAR();
.LBB0_220:
	ds_read_b128 v[64:67], v197 offset:32768
	ds_read_b128 v[68:71], v197 offset:40960
	ds_read_b128 v[222:225], v198 offset:32768
	ds_read_b128 v[244:247], v198 offset:40960
	v_exp_f32_e32 v226, v84
	v_exp_f32_e32 v227, v85
	s_waitcnt lgkmcnt(3)
	v_mfma_f32_32x32x16_bf16 v[96:111], v[64:67], v[126:129], 0
	v_exp_f32_e32 v234, v86
	v_exp_f32_e32 v235, v87
	v_exp_f32_e32 v236, v88
	v_exp_f32_e32 v237, v89
	v_exp_f32_e32 v238, v90
	v_exp_f32_e32 v239, v91
	v_exp_f32_e32 v240, v92
	s_waitcnt lgkmcnt(2)
	v_mfma_f32_32x32x16_bf16 v[64:79], v[68:71], v[126:129], 0
	v_exp_f32_e32 v241, v93
	v_exp_f32_e32 v95, v95
	s_waitcnt lgkmcnt(1)
	v_mfma_f32_32x32x16_bf16 v[96:111], v[222:225], v[122:125], v[96:111]
	s_waitcnt lgkmcnt(0)
	v_mfma_f32_32x32x16_bf16 v[64:79], v[244:247], v[122:125], v[64:79]
	ds_read_b128 v[222:225], v199 offset:32768
	ds_read_b128 v[244:247], v199 offset:40960
	s_waitcnt lgkmcnt(1)
	v_mfma_f32_32x32x16_bf16 v[96:111], v[222:225], v[118:121], v[96:111]
	s_waitcnt lgkmcnt(0)
	v_mfma_f32_32x32x16_bf16 v[64:79], v[244:247], v[118:121], v[64:79]
	ds_read_b128 v[222:225], v196 offset:32768
	ds_read_b128 v[244:247], v196 offset:40960
	s_waitcnt lgkmcnt(1)
	v_mfma_f32_32x32x16_bf16 v[96:111], v[222:225], v[114:117], v[96:111]
	v_exp_f32_e32 v222, v80
	v_add_f32_e32 v80, 0, v219
	v_add_f32_e32 v80, v221, v80
	v_add_f32_e32 v80, v217, v80
	v_add_f32_e32 v80, v220, v80
	v_add_f32_e32 v80, v215, v80
	v_add_f32_e32 v80, v218, v80
	v_add_f32_e32 v80, v214, v80
	v_add_f32_e32 v80, v216, v80
	v_add_f32_e32 v80, v211, v80
	v_add_f32_e32 v80, v213, v80
	v_add_f32_e32 v80, v209, v80
	v_add_f32_e32 v80, v212, v80
	v_add_f32_e32 v80, v207, v80
	v_exp_f32_e32 v223, v81
	v_add_f32_e32 v80, v210, v80
	v_exp_f32_e32 v224, v82
	v_add_f32_e32 v80, v206, v80
	v_exp_f32_e32 v225, v83
	v_add_f32_e32 v80, v208, v80
	v_add_f32_e32 v80, v222, v80
	v_add_f32_e32 v80, v223, v80
	v_add_f32_e32 v80, v224, v80
	v_add_f32_e32 v80, v225, v80
	v_add_f32_e32 v80, v226, v80
	v_add_f32_e32 v80, v227, v80
	v_add_f32_e32 v80, v234, v80
	v_add_f32_e32 v80, v235, v80
	v_add_f32_e32 v80, v236, v80
	v_add_f32_e32 v80, v237, v80
	s_waitcnt lgkmcnt(0)
	v_mfma_f32_32x32x16_bf16 v[64:79], v[244:247], v[114:117], v[64:79]
	v_exp_f32_e32 v244, v94
	v_add_f32_e32 v80, v238, v80
	v_add_f32_e32 v80, v239, v80
	v_add_f32_e32 v80, v240, v80
	v_add_f32_e32 v80, v241, v80
	v_add_f32_e32 v80, v244, v80
	v_add_f32_e32 v204, v95, v80
	v_mov_b32_e32 v205, v204
	v_cvt_pk_bf16_f32 v80, v219, v221
	v_cvt_pk_bf16_f32 v81, v217, v220
	v_cvt_pk_bf16_f32 v82, v215, v218
	v_cvt_pk_bf16_f32 v83, v214, v216
	v_cvt_pk_bf16_f32 v84, v211, v213
	v_cvt_pk_bf16_f32 v85, v209, v212
	v_cvt_pk_bf16_f32 v86, v207, v210
	v_cvt_pk_bf16_f32 v87, v206, v208
	v_cvt_pk_bf16_f32 v88, v222, v223
	v_cvt_pk_bf16_f32 v89, v224, v225
	v_cvt_pk_bf16_f32 v90, v226, v227
	v_cvt_pk_bf16_f32 v91, v234, v235
	v_cvt_pk_bf16_f32 v92, v236, v237
	v_cvt_pk_bf16_f32 v93, v238, v239
	v_cvt_pk_bf16_f32 v94, v240, v241
	v_cvt_pk_bf16_f32 v95, v244, v95
	s_nop 1
	v_permlane32_swap_b32_e32 v204, v205
	v_permlane32_swap_b32_e32 v80, v82
	v_permlane32_swap_b32_e32 v81, v83
	v_permlane32_swap_b32_e32 v84, v86
	v_permlane32_swap_b32_e32 v85, v87
	v_permlane32_swap_b32_e32 v88, v90
	v_permlane32_swap_b32_e32 v89, v91
	v_permlane32_swap_b32_e32 v92, v94
	v_permlane32_swap_b32_e32 v93, v95
	s_cmp_ge_u32 s40, s39
	s_cselect_b64 s[18:19], -1, 0
	s_and_b64 vcc, exec, s[18:19]
	s_cbranch_vccnz .Ldiff_pf_skip
	v_add_co_u32_e32 v130, vcc, 0x13281000, v174
	s_nop 1
	v_addc_co_u32_e32 v131, vcc, 0, v175, vcc
	v_add_co_u32_e32 v134, vcc, 0x132b1000, v174
	s_nop 1
	v_addc_co_u32_e32 v135, vcc, 0, v175, vcc
	v_add_co_u32_e32 v138, vcc, 0x13280000, v176
	global_load_dwordx4 v[130:133], v[130:131], off
	s_nop 0
	global_load_dwordx4 v[134:137], v[134:135], off
	v_addc_co_u32_e32 v139, vcc, 0, v177, vcc
	global_load_dwordx4 v[138:141], v[138:139], off offset:2048

; #define SBAR() __builtin_amdgcn_sched_barrier(0)
; template <int OFF> __device__ __forceinline__ s16x4 tr_read(int vb) {
;   s16x4 r; asm volatile("ds_read_b64_tr_b16 %0, %1 offset:%2" : "=&v"(r) : "v"(vb), "i"(OFF) : "memory"); return r;
; }
; template <int D0> __device__ __forceinline__ void pv_one(f32x16& od, int vb, bf16x8 pa0, bf16x8 pa1, bf16x8 pa2, bf16x8 pa3) {
;   const s16x4 l0 = tr_read<v_rd_off(D0, 0, 0)>(vb), h0 = tr_read<v_rd_off(D0, 0, 1)>(vb), l1 = tr_read<v_rd_off(D0, 1, 0)>(vb), h1 = tr_read<v_rd_off(D0, 1, 1)>(vb);
;   const s16x4 l2 = tr_read<v_rd_off(D0, 2, 0)>(vb), h2 = tr_read<v_rd_off(D0, 2, 1)>(vb), l3 = tr_read<v_rd_off(D0, 3, 0)>(vb), h3 = tr_read<v_rd_off(D0, 3, 1)>(vb);
;   asm volatile("s_waitcnt lgkmcnt(0)" ::: "memory"); SBAR();
;     ...
;   od = __builtin_amdgcn_mfma_f32_32x32x16_bf16(pa0, PK(l0, h0), od, 0, 0, 0);
;   od = __builtin_amdgcn_mfma_f32_32x32x16_bf16(pa1, PK(l1, h1), od, 0, 0, 0);
;   od = __builtin_amdgcn_mfma_f32_32x32x16_bf16(pa2, PK(l2, h2), od, 0, 0, 0);
;   od = __builtin_amdgcn_mfma_f32_32x32x16_bf16(pa3, PK(l3, h3), od, 0, 0, 0);
;     ...
; }
; __device__ __forceinline__ void pv_d0(f32x16* o, int vb, bf16x8 pa0, bf16x8 pa1, bf16x8 pa2, bf16x8 pa3) {
;   pv_one<0>(o[0], vb, pa0, pa1, pa2, pa3); pv_one<1>(o[1], vb, pa0, pa1, pa2, pa3); pv_one<2>(o[2], vb, pa0, pa1, pa2, pa3); pv_one<3>(o[3], vb, pa0, pa1, pa2, pa3);
.LBB0_223:
	v_max_f32_e32 v252, v97, v97
	v_max_f32_e32 v253, v96, v96
	v_max_f32_e32 v252, v253, v252
	v_max3_f32 v252, v252, v98, v99
	v_max3_f32 v252, v252, v100, v101
	v_max3_f32 v252, v252, v102, v103
	v_max3_f32 v252, v252, v104, v105
	v_max3_f32 v252, v252, v106, v107
	v_max3_f32 v252, v252, v108, v109
	v_max3_f32 v252, v252, v110, v111
	v_max3_f32 v252, v252, v64, v65
	v_max3_f32 v252, v252, v66, v67
	v_max3_f32 v252, v252, v68, v69
	v_max3_f32 v252, v252, v70, v71
	v_max3_f32 v252, v252, v72, v73
	v_max3_f32 v252, v252, v74, v75
	v_max3_f32 v252, v252, v76, v77
	v_max3_f32 v252, v252, v78, v79
	v_mov_b32_e32 v253, v252
	s_nop 1
	v_permlane32_swap_b32_e32 v252, v253
	v_max_f32_e32 v253, v253, v253
	v_max_f32_e32 v252, v252, v252
	v_max_f32_e32 v252, v252, v253
	s_nop 0
	s_waitcnt lgkmcnt(6)
	v_mfma_f32_32x32x16_bf16 v[0:15], v[80:83], v[174:177], v[0:15]
	ds_read_b64_tr_b16 v[174:175], v190 offset:0x200
	ds_read_b64_tr_b16 v[176:177], v190 offset:0xa00
	s_waitcnt lgkmcnt(6)
	v_mfma_f32_32x32x16_bf16 v[0:15], v[84:87], v[206:209], v[0:15]
	ds_read_b64_tr_b16 v[206:207], v190 offset:0x1200
	ds_read_b64_tr_b16 v[208:209], v190 offset:0x1a00
	s_waitcnt lgkmcnt(6)
	v_mfma_f32_32x32x16_bf16 v[0:15], v[88:91], v[210:213], v[0:15]
	ds_read_b64_tr_b16 v[210:211], v190 offset:0x2200
	ds_read_b64_tr_b16 v[212:213], v190 offset:0x2a00
	s_waitcnt lgkmcnt(6)
	v_mfma_f32_32x32x16_bf16 v[0:15], v[92:95], v[214:217], v[0:15]
	ds_read_b64_tr_b16 v[214:215], v190 offset:0x3200
	ds_read_b64_tr_b16 v[216:217], v190 offset:0x3a00
	s_waitcnt lgkmcnt(6)
	v_mfma_f32_32x32x16_bf16 v[48:63], v[80:83], v[174:177], v[48:63]
	ds_read_b64_tr_b16 v[174:175], v190 offset:0x400
	ds_read_b64_tr_b16 v[176:177], v190 offset:0xc00
	s_waitcnt lgkmcnt(6)
	v_mfma_f32_32x32x16_bf16 v[48:63], v[84:87], v[206:209], v[48:63]
	ds_read_b64_tr_b16 v[206:207], v190 offset:0x1400
	ds_read_b64_tr_b16 v[208:209], v190 offset:0x1c00
	s_waitcnt lgkmcnt(6)
	v_mfma_f32_32x32x16_bf16 v[48:63], v[88:91], v[210:213], v[48:63]
	ds_read_b64_tr_b16 v[210:211], v190 offset:0x2400
	ds_read_b64_tr_b16 v[212:213], v190 offset:0x2c00
	s_waitcnt lgkmcnt(6)
	v_mfma_f32_32x32x16_bf16 v[48:63], v[92:95], v[214:217], v[48:63]
	ds_read_b64_tr_b16 v[214:215], v190 offset:0x3400
	ds_read_b64_tr_b16 v[216:217], v190 offset:0x3c00
	s_waitcnt lgkmcnt(6)
	v_mfma_f32_32x32x16_bf16 v[32:47], v[80:83], v[174:177], v[32:47]
	ds_read_b64_tr_b16 v[174:175], v190 offset:0x600
	ds_read_b64_tr_b16 v[176:177], v190 offset:0xe00
	s_waitcnt lgkmcnt(6)
	v_mfma_f32_32x32x16_bf16 v[32:47], v[84:87], v[206:209], v[32:47]
	ds_read_b64_tr_b16 v[206:207], v190 offset:0x1600
	ds_read_b64_tr_b16 v[208:209], v190 offset:0x1e00
	s_waitcnt lgkmcnt(6)
	v_mfma_f32_32x32x16_bf16 v[32:47], v[88:91], v[210:213], v[32:47]
	ds_read_b64_tr_b16 v[210:211], v190 offset:0x2600
	ds_read_b64_tr_b16 v[212:213], v190 offset:0x2e00
	s_waitcnt lgkmcnt(6)
	v_mfma_f32_32x32x16_bf16 v[32:47], v[92:95], v[214:217], v[32:47]
	ds_read_b64_tr_b16 v[214:215], v190 offset:0x3600
	ds_read_b64_tr_b16 v[216:217], v190 offset:0x3e00
	s_waitcnt lgkmcnt(6)
	v_mfma_f32_32x32x16_bf16 v[16:31], v[80:83], v[174:177], v[16:31]
	s_waitcnt vmcnt(3)
	ds_write_b128 v195, v[150:153] offset:49152
	s_waitcnt lgkmcnt(5)
	v_mfma_f32_32x32x16_bf16 v[16:31], v[84:87], v[206:209], v[16:31]
	s_waitcnt lgkmcnt(3)
	v_mfma_f32_32x32x16_bf16 v[16:31], v[88:91], v[210:213], v[16:31]
	s_waitcnt lgkmcnt(1)
	v_mfma_f32_32x32x16_bf16 v[16:31], v[92:95], v[214:217], v[16:31]
	v_cmp_ge_f32_e32 vcc, s45, v252
	s_cmp_eq_u64 vcc, exec
	v_mov_b32_e32 v150, 1.0
	s_cbranch_scc0 .LBB0_233
.LBB0_224:
	v_exp_f32_e32 v176, v96
	v_exp_f32_e32 v206, v97
	v_exp_f32_e32 v174, v98
	v_exp_f32_e32 v177, v99
	v_exp_f32_e32 v152, v100
	v_exp_f32_e32 v175, v101
	v_exp_f32_e32 v151, v102
	v_exp_f32_e32 v153, v103
	s_waitcnt lgkmcnt(0)
	s_barrier
	s_waitcnt vmcnt(3)
	v_cmp_gt_f32_e32 vcc, 1.0, v150
	ds_write_b128 v193, v[142:145] offset:16384
	ds_write_b128 v194, v[146:149] offset:16384
	s_cbranch_vccz .LBB0_228
	s_and_saveexec_b64 s[20:21], s[6:7]
	ds_write_b32 v187, v150 offset:128
	s_or_b64 exec, exec, s[20:21]
	s_waitcnt lgkmcnt(0)
	v_add_u32_e32 v92, v161, v112
	ds_read_b128 v[80:83], v92 offset:224
	ds_read_b128 v[84:87], v92 offset:192
	ds_read_b128 v[88:91], v92 offset:160
	ds_read_b128 v[92:95], v92 offset:128
	s_waitcnt lgkmcnt(3)
	v_pk_mul_f32 v[12:13], v[12:13], v[80:81]
	s_waitcnt lgkmcnt(2)
	v_pk_mul_f32 v[8:9], v[8:9], v[84:85]
	s_waitcnt lgkmcnt(1)
	v_pk_mul_f32 v[4:5], v[4:5], v[88:89]
	v_pk_mul_f32 v[14:15], v[14:15], v[82:83]
	v_pk_mul_f32 v[10:11], v[10:11], v[86:87]
	v_pk_mul_f32 v[6:7], v[6:7], v[90:91]
	s_waitcnt lgkmcnt(0)
	v_pk_mul_f32 v[2:3], v[2:3], v[94:95]
	v_pk_mul_f32 v[0:1], v[0:1], v[92:93]
	v_pk_mul_f32 v[60:61], v[60:61], v[80:81]
	v_pk_mul_f32 v[56:57], v[56:57], v[84:85]
	v_pk_mul_f32 v[52:53], v[52:53], v[88:89]
	v_pk_mul_f32 v[62:63], v[62:63], v[82:83]
	v_pk_mul_f32 v[58:59], v[58:59], v[86:87]
	v_pk_mul_f32 v[54:55], v[54:55], v[90:91]
	v_pk_mul_f32 v[50:51], v[50:51], v[94:95]
	v_pk_mul_f32 v[48:49], v[48:49], v[92:93]
	v_pk_mul_f32 v[44:45], v[44:45], v[80:81]
	v_pk_mul_f32 v[40:41], v[40:41], v[84:85]
	v_pk_mul_f32 v[36:37], v[36:37], v[88:89]
	v_pk_mul_f32 v[46:47], v[46:47], v[82:83]
	v_pk_mul_f32 v[42:43], v[42:43], v[86:87]
	v_pk_mul_f32 v[38:39], v[38:39], v[90:91]
	v_pk_mul_f32 v[34:35], v[34:35], v[94:95]
	v_pk_mul_f32 v[32:33], v[32:33], v[92:93]
	v_pk_mul_f32 v[28:29], v[28:29], v[80:81]
	v_pk_mul_f32 v[24:25], v[24:25], v[84:85]
	v_pk_mul_f32 v[20:21], v[20:21], v[88:89]
	v_pk_mul_f32 v[30:31], v[30:31], v[82:83]
	v_pk_mul_f32 v[26:27], v[26:27], v[86:87]
	v_pk_mul_f32 v[22:23], v[22:23], v[90:91]
	v_pk_mul_f32 v[18:19], v[18:19], v[94:95]
	v_pk_mul_f32 v[16:17], v[16:17], v[92:93]
.LBB0_228:
	v_add_f32_e32 v80, v201, v202
	v_fmac_f32_e32 v80, v200, v189
	v_add_f32_e32 v189, v204, v205
	v_fmac_f32_e32 v189, v80, v203
	ds_read_b128 v[80:83], v197 offset:49152
	ds_read_b128 v[84:87], v197 offset:57344
	v_exp_f32_e32 v147, v104
	v_exp_f32_e32 v149, v105
	v_exp_f32_e32 v145, v106
	v_exp_f32_e32 v148, v107
	v_exp_f32_e32 v143, v108
	v_exp_f32_e32 v146, v109
	v_exp_f32_e32 v142, v110
	v_exp_f32_e32 v144, v111
	v_lshl_add_u64 v[170:171], v[170:171], 0, s[46:47]
	v_lshl_add_u64 v[172:173], v[172:173], 0, s[46:47]
	s_add_i32 s40, s40, 2
	s_and_b64 vcc, exec, s[18:19]
	s_cbranch_vccnz .LBB0_234
	v_mov_b32_e32 v200, v150
	s_branch .LBB0_214
